# v35 minus the dead VALU->MFMA pad (s_nop 0) at the first half-tile head (its C-operand init now sits before the barrier)
# speedup vs baseline: 1.0030x; 1.0030x over previous
; #define LAS __attribute__((address_space(3)))
; template <int HF> ...
;     ...
;         for (int r = 0; r < 16; ++r) p[r] = __builtin_fmaf(s2v, (float)((r & 3) + 8 * (r >> 2)), tb);
; #pragma unroll
;         for (int d0 = 0; d0 < 4; ++d0) { const bf16x8 kf = *(const LAS bf16x8*)(kb + HF * 32 * KROW + sub * 128 + d0 * 32);
;             p = __builtin_amdgcn_mfma_f32_32x32x16_bf16(kf, qf[sub][d0], p, 0, 0, 0); }
;         if (band) { const int lim = qw0 + r32 - (kvh0 + 4 * hi);
;             asm volatile("s_nop 15" : "+v"(p));
;             const float ninf = -INFINITY;
; #pragma unroll
;             for (int r = 0; r < 16; ++r) asm("v_cmp_gt_i32_e32 vcc, %2, %1\n\tv_cndmask_b32_e32 %0, %0, %3, vcc" : "+v"(p[r]) : "v"(lim), "i"((r & 3) + 8 * (r >> 2)), "v"(ninf) : "vcc"); }
.LBB0_251:
	s_andn2_b64 vcc, exec, s[66:67]
	s_cbranch_vccnz .LBB0_259
	ds_read_b128 v[248:251], v247
	ds_read_b128 v[252:255], v247 offset:32
	s_and_b64 vcc, exec, s[10:11]
	s_waitcnt vmcnt(7) lgkmcnt(1)
	v_mfma_f32_32x32x16_bf16 v[144:159], v[248:251], v[176:179], v[128:143]
	s_waitcnt vmcnt(6) lgkmcnt(0)
	v_mfma_f32_32x32x16_bf16 v[144:159], v[252:255], v[180:183], v[144:159]
	ds_read_b128 v[248:251], v247 offset:64
	ds_read_b128 v[252:255], v247 offset:96
	s_waitcnt vmcnt(5) lgkmcnt(1)
	v_mfma_f32_32x32x16_bf16 v[144:159], v[248:251], v[184:187], v[144:159]
	s_waitcnt vmcnt(4) lgkmcnt(0)
	v_mfma_f32_32x32x16_bf16 v[144:159], v[252:255], v[188:191], v[144:159]
	s_cbranch_vccnz .LBB0_254
	s_nop 15
	s_nop 0
	v_cmp_gt_i32_e32 vcc, 0, v227
	v_cndmask_b32_e32 v144, v144, v244, vcc
	s_nop 0
	v_cmp_gt_i32_e32 vcc, 1, v227
	v_cndmask_b32_e32 v145, v145, v244, vcc
	s_nop 0
	v_cmp_gt_i32_e32 vcc, 2, v227
	v_cndmask_b32_e32 v146, v146, v244, vcc
	s_nop 0
	v_cmp_gt_i32_e32 vcc, 3, v227
	v_cndmask_b32_e32 v147, v147, v244, vcc
	s_nop 0
	v_cmp_gt_i32_e32 vcc, 8, v227
	v_cndmask_b32_e32 v148, v148, v244, vcc
	s_nop 0
	v_cmp_gt_i32_e32 vcc, 9, v227
	v_cndmask_b32_e32 v149, v149, v244, vcc
	s_nop 0
	v_cmp_gt_i32_e32 vcc, 10, v227
	v_cndmask_b32_e32 v150, v150, v244, vcc
	s_nop 0
	v_cmp_gt_i32_e32 vcc, 11, v227
	v_cndmask_b32_e32 v151, v151, v244, vcc
	s_nop 0
	v_cmp_gt_i32_e32 vcc, 16, v227
	v_cndmask_b32_e32 v152, v152, v244, vcc
	s_nop 0
	v_cmp_gt_i32_e32 vcc, 17, v227
	v_cndmask_b32_e32 v153, v153, v244, vcc
	s_nop 0
	v_cmp_gt_i32_e32 vcc, 18, v227
	v_cndmask_b32_e32 v154, v154, v244, vcc
	s_nop 0
	v_cmp_gt_i32_e32 vcc, 19, v227
	v_cndmask_b32_e32 v155, v155, v244, vcc
	s_nop 0
	v_cmp_gt_i32_e32 vcc, 24, v227
	v_cndmask_b32_e32 v156, v156, v244, vcc
	s_nop 0
	v_cmp_gt_i32_e32 vcc, 25, v227
	v_cndmask_b32_e32 v157, v157, v244, vcc
	s_nop 0
	v_cmp_gt_i32_e32 vcc, 26, v227
	v_cndmask_b32_e32 v158, v158, v244, vcc
	s_nop 0
	v_cmp_gt_i32_e32 vcc, 27, v227
	v_cndmask_b32_e32 v159, v159, v244, vcc
